# staging-row L2 prefetch restricted to waves 4-7 (prefetched set fits the XCD L2)
# speedup vs baseline: 1.0013x; 1.0013x over previous
.LBB0_282:
	s_or_b64 exec, exec, s[4:5]
	v_and_b32_e32 v49, 0xffff0000, v14
	v_lshlrev_b32_e32 v48, 16, v14
	v_lshlrev_b32_e32 v39, 16, v6
	v_and_b32_e32 v38, 0xffff0000, v6
	v_lshlrev_b32_e32 v37, 16, v7
	v_and_b32_e32 v36, 0xffff0000, v7
	v_lshlrev_b32_e32 v7, 16, v9
	v_and_b32_e32 v6, 0xffff0000, v9
	v_mul_f32_e32 v9, v49, v49
	v_lshlrev_b32_e32 v54, 16, v15
	v_fmac_f32_e32 v9, v48, v48
	v_and_b32_e32 v55, 0xffff0000, v15
	v_fmac_f32_e32 v9, v54, v54
	v_lshlrev_b32_e32 v56, 16, v16
	v_fmac_f32_e32 v9, v55, v55
	v_and_b32_e32 v57, 0xffff0000, v16
	v_fmac_f32_e32 v9, v56, v56
	v_lshlrev_b32_e32 v58, 16, v17
	v_fmac_f32_e32 v9, v57, v57
	v_and_b32_e32 v59, 0xffff0000, v17
	v_fmac_f32_e32 v9, v58, v58
	v_lshlrev_b32_e32 v47, 16, v10
	v_fmac_f32_e32 v9, v59, v59
	v_and_b32_e32 v46, 0xffff0000, v10
	v_fmac_f32_e32 v9, v47, v47
	v_lshlrev_b32_e32 v45, 16, v11
	v_fmac_f32_e32 v9, v46, v46
	v_and_b32_e32 v44, 0xffff0000, v11
	v_fmac_f32_e32 v9, v45, v45
	v_lshlrev_b32_e32 v43, 16, v12
	v_fmac_f32_e32 v9, v44, v44
	v_and_b32_e32 v42, 0xffff0000, v12
	v_fmac_f32_e32 v9, v43, v43
	v_lshlrev_b32_e32 v41, 16, v13
	v_fmac_f32_e32 v9, v42, v42
	v_and_b32_e32 v40, 0xffff0000, v13
	v_fmac_f32_e32 v9, v41, v41
	v_fmac_f32_e32 v9, v40, v40
	v_fmac_f32_e32 v9, v39, v39
	v_fmac_f32_e32 v9, v38, v38
	v_fmac_f32_e32 v9, v37, v37
	v_lshlrev_b32_e32 v35, 16, v8
	v_fmac_f32_e32 v9, v36, v36
	v_and_b32_e32 v8, 0xffff0000, v8
	v_fmac_f32_e32 v9, v35, v35
	v_fmac_f32_e32 v9, v8, v8
	v_fmac_f32_e32 v9, v7, v7
	v_lshlrev_b32_e32 v17, 16, v2
	v_fmac_f32_e32 v9, v6, v6
	v_and_b32_e32 v16, 0xffff0000, v2
	v_fmac_f32_e32 v9, v17, v17
	v_lshlrev_b32_e32 v15, 16, v3
	v_fmac_f32_e32 v9, v16, v16
	v_and_b32_e32 v14, 0xffff0000, v3
	v_fmac_f32_e32 v9, v15, v15
	v_and_b32_e32 v12, 0xffff0000, v4
	v_lshlrev_b32_e32 v13, 16, v4
	v_fmac_f32_e32 v9, v14, v14
	v_pk_mul_f32 v[2:3], v[12:13], v[12:13]
	v_and_b32_e32 v10, 0xffff0000, v5
	v_add_f32_e32 v3, v3, v9
	v_lshlrev_b32_e32 v11, 16, v5
	v_add_f32_e32 v4, v2, v3
	v_pk_mul_f32 v[2:3], v[10:11], v[10:11]
	s_lshl_b32 s0, s15, 2
	v_add_f32_e32 v3, v3, v4
	v_add_f32_e32 v2, v2, v3
	ds_bpermute_b32 v3, v199, v2
	v_mov_b32_e32 v34, s0
	s_waitcnt lgkmcnt(0)
	s_barrier
	v_add_f32_e32 v2, v2, v3
	v_fmamk_f32 v2, v2, 0x3c800000, v202
	v_rsq_f32_e32 v2, v2
	global_load_dword v170, v34, s[10:11]
	v_mul_f32_e32 v34, 0x3e38aa3b, v2
	v_mov_b64_e32 v[2:3], v[220:221]
	v_mov_b64_e32 v[4:5], v[222:223]
	v_mov_b64_e32 v[50:51], v[216:217]
	v_mov_b64_e32 v[52:53], v[218:219]
	v_mul_f32_e32 v9, v34, v48
	v_mul_f32_e32 v48, v34, v49
	v_mul_f32_e32 v46, v34, v46
	v_mul_f32_e32 v44, v34, v44
	v_mul_f32_e32 v38, v34, v38
	v_mul_f32_e32 v36, v34, v36
	v_mul_f32_e32 v8, v34, v8
	v_mul_f32_e32 v17, v34, v17
	v_mul_f32_e32 v16, v34, v16
	s_waitcnt vmcnt(0)
	v_mul_f32_e32 v9, v50, v9
	v_mul_f32_e32 v48, v51, v48
	v_cvt_pk_bf16_f32 v50, v9, v48
	v_mul_f32_e32 v9, v34, v54
	v_mul_f32_e32 v9, v52, v9
	v_mul_f32_e32 v48, v34, v55
	v_mul_f32_e32 v48, v53, v48
	v_cvt_pk_bf16_f32 v51, v9, v48
	v_mul_f32_e32 v9, v34, v56
	v_mul_f32_e32 v2, v2, v9
	v_mul_f32_e32 v9, v34, v57
	v_mul_f32_e32 v3, v3, v9
	v_cvt_pk_bf16_f32 v52, v2, v3
	v_mul_f32_e32 v2, v34, v58
	v_mul_f32_e32 v3, v34, v59
	v_mul_f32_e32 v2, v4, v2
	v_mul_f32_e32 v3, v5, v3
	v_cvt_pk_bf16_f32 v53, v2, v3
	v_mov_b64_e32 v[2:3], v[228:229]
	v_mov_b64_e32 v[4:5], v[230:231]
	v_mov_b64_e32 v[54:55], v[224:225]
	v_mov_b64_e32 v[56:57], v[226:227]
	v_mul_f32_e32 v9, v34, v47
	s_waitcnt vmcnt(0)
	v_mul_f32_e32 v9, v9, v54
	v_mul_f32_e32 v46, v46, v55
	v_cvt_pk_bf16_f32 v54, v9, v46
	v_mul_f32_e32 v9, v34, v45
	v_mul_f32_e32 v9, v9, v56
	v_mul_f32_e32 v44, v44, v57
	v_cvt_pk_bf16_f32 v55, v9, v44
	v_mul_f32_e32 v9, v34, v43
	v_mul_f32_e32 v2, v9, v2
	v_mul_f32_e32 v9, v34, v42
	v_mul_f32_e32 v3, v9, v3
	v_cvt_pk_bf16_f32 v56, v2, v3
	v_mul_f32_e32 v2, v34, v41
	v_mul_f32_e32 v3, v34, v40
	v_mul_f32_e32 v2, v2, v4
	v_mul_f32_e32 v3, v3, v5
	v_cvt_pk_bf16_f32 v57, v2, v3
	v_mov_b64_e32 v[2:3], v[236:237]
	v_mov_b64_e32 v[4:5], v[238:239]
	v_mov_b64_e32 v[40:41], v[232:233]
	v_mov_b64_e32 v[42:43], v[234:235]
	v_mul_f32_e32 v9, v34, v39
	s_waitcnt vmcnt(1)
	v_mul_f32_e32 v3, v8, v3
	s_waitcnt vmcnt(0)
	v_mul_f32_e32 v9, v9, v40
	v_mul_f32_e32 v38, v38, v41
	v_cvt_pk_bf16_f32 v58, v9, v38
	v_mul_f32_e32 v9, v34, v37
	v_mul_f32_e32 v9, v9, v42
	v_mul_f32_e32 v36, v36, v43
	v_cvt_pk_bf16_f32 v59, v9, v36
	v_mul_f32_e32 v9, v34, v35
	v_mul_f32_e32 v2, v9, v2
	v_cvt_pk_bf16_f32 v60, v2, v3
	v_mul_f32_e32 v2, v34, v7
	v_mul_f32_e32 v3, v34, v6
	v_mul_f32_e32 v2, v2, v4
	v_mul_f32_e32 v3, v3, v5
	v_cvt_pk_bf16_f32 v61, v2, v3
	v_mov_b64_e32 v[2:3], v[248:249]
	v_mov_b64_e32 v[4:5], v[250:251]
	v_mov_b64_e32 v[6:7], v[240:241]
	v_mov_b64_e32 v[8:9], v[242:243]
	s_waitcnt vmcnt(0)
	v_mul_f32_e32 v6, v17, v6
	v_mul_f32_e32 v7, v16, v7
	v_cvt_pk_bf16_f32 v82, v6, v7
	v_mul_f32_e32 v6, v34, v15
	v_mul_f32_e32 v6, v6, v8
	v_mul_f32_e32 v7, v34, v14
	v_mul_f32_e32 v7, v7, v9
	v_cvt_pk_bf16_f32 v83, v6, v7
	v_mul_f32_e32 v6, v34, v13
	v_mul_f32_e32 v2, v6, v2
	v_mul_f32_e32 v6, v34, v12
	v_mul_f32_e32 v3, v6, v3
	v_cvt_pk_bf16_f32 v84, v2, v3
	v_mul_f32_e32 v2, v34, v11
	v_mul_f32_e32 v3, v34, v10
	v_mul_f32_e32 v2, v2, v4
	v_mul_f32_e32 v3, v3, v5
	v_cvt_pk_bf16_f32 v85, v2, v3
	s_setprio 1
	v_or_b32_e32 v2, s17, v1
	v_mad_u32_u24 v189, v2, s6, v195
	ds_read_b128 v[2:5], v189
	v_or_b32_e32 v6, s18, v1
	v_mad_u32_u24 v62, v6, s6, v195
	s_add_i32 s19, s14, 2
	s_add_i32 s18, s14, 3
	s_or_b32 s0, s14, 4
	s_waitcnt lgkmcnt(0)
	v_mfma_f32_32x32x16_bf16 v[146:161], v[2:5], v[50:53], 0
	ds_read_b128 v[2:5], v189 offset:32
	s_waitcnt lgkmcnt(0)
	v_mfma_f32_32x32x16_bf16 v[146:161], v[2:5], v[54:57], v[146:161]
	ds_read_b128 v[2:5], v189 offset:64
	s_waitcnt lgkmcnt(0)
	v_mfma_f32_32x32x16_bf16 v[146:161], v[2:5], v[58:61], v[146:161]
	ds_read_b128 v[2:5], v189 offset:96
	s_waitcnt lgkmcnt(0)
	v_mfma_f32_32x32x16_bf16 v[146:161], v[2:5], v[82:85], v[146:161]
	ds_read_b128 v[2:5], v62
	s_waitcnt lgkmcnt(0)
	v_mfma_f32_32x32x16_bf16 v[66:81], v[2:5], v[50:53], 0
	ds_read_b128 v[2:5], v62 offset:32
	s_waitcnt lgkmcnt(0)
	v_mfma_f32_32x32x16_bf16 v[66:81], v[2:5], v[54:57], v[66:81]
	ds_read_b128 v[2:5], v62 offset:64
	s_waitcnt lgkmcnt(0)
	v_mfma_f32_32x32x16_bf16 v[66:81], v[2:5], v[58:61], v[66:81]
	ds_read_b128 v[2:5], v62 offset:96
	s_waitcnt lgkmcnt(0)
	v_mfma_f32_32x32x16_bf16 v[66:81], v[2:5], v[82:85], v[66:81]
	v_lshl_or_b32 v2, s19, 5, v1
	v_mad_u32_u24 v6, v2, s6, v195
	ds_read_b128 v[2:5], v6
	s_waitcnt lgkmcnt(0)
	v_mfma_f32_32x32x16_bf16 v[34:49], v[2:5], v[50:53], 0
	ds_read_b128 v[2:5], v6 offset:32
	s_waitcnt lgkmcnt(0)
	v_mfma_f32_32x32x16_bf16 v[34:49], v[2:5], v[54:57], v[34:49]
	ds_read_b128 v[2:5], v6 offset:64
	s_waitcnt lgkmcnt(0)
	v_mfma_f32_32x32x16_bf16 v[34:49], v[2:5], v[58:61], v[34:49]
	ds_read_b128 v[2:5], v6 offset:96
	s_waitcnt lgkmcnt(0)
	v_mfma_f32_32x32x16_bf16 v[34:49], v[2:5], v[82:85], v[34:49]
	v_lshl_or_b32 v2, s18, 5, v1
	v_mad_u32_u24 v63, v2, s6, v195
	ds_read_b128 v[2:5], v63
	ds_read_b128 v[86:89], v63 offset:32
	s_waitcnt lgkmcnt(1)
	v_mfma_f32_32x32x16_bf16 v[2:17], v[2:5], v[50:53], 0
	s_waitcnt lgkmcnt(0)
	v_mfma_f32_32x32x16_bf16 v[2:17], v[86:89], v[54:57], v[2:17]
	ds_read_b128 v[86:89], v63 offset:64
	s_waitcnt lgkmcnt(0)
	v_mfma_f32_32x32x16_bf16 v[2:17], v[86:89], v[58:61], v[2:17]
	ds_read_b128 v[86:89], v63 offset:96
	v_lshl_or_b32 v63, s0, 5, v1
	v_mad_u32_u24 v63, v63, s6, v195
	s_waitcnt lgkmcnt(0)
	v_mfma_f32_32x32x16_bf16 v[2:17], v[86:89], v[82:85], v[2:17]
	ds_read_b128 v[86:89], v63
	s_waitcnt lgkmcnt(0)
	v_mfma_f32_32x32x16_bf16 v[98:113], v[86:89], v[50:53], 0
	ds_read_b128 v[50:53], v63 offset:32
	s_waitcnt lgkmcnt(0)
	v_mfma_f32_32x32x16_bf16 v[98:113], v[50:53], v[54:57], v[98:113]
	ds_read_b128 v[50:53], v63 offset:64
	s_waitcnt lgkmcnt(0)
	v_mfma_f32_32x32x16_bf16 v[98:113], v[50:53], v[58:61], v[98:113]
	ds_read_b128 v[50:53], v63 offset:96
	s_waitcnt lgkmcnt(0)
	v_mfma_f32_32x32x16_bf16 v[98:113], v[50:53], v[82:85], v[98:113]
	s_setprio 0
	v_and_b32_e32 v86, 0xffff0000, v30
	v_lshlrev_b32_e32 v65, 16, v30
	v_lshlrev_b32_e32 v55, 16, v22
	v_and_b32_e32 v54, 0xffff0000, v22
	v_lshlrev_b32_e32 v53, 16, v23
	v_and_b32_e32 v52, 0xffff0000, v23
	v_lshlrev_b32_e32 v23, 16, v25
	v_and_b32_e32 v22, 0xffff0000, v25
	v_mul_f32_e32 v25, v86, v86
	v_lshlrev_b32_e32 v87, 16, v31
	v_fmac_f32_e32 v25, v65, v65
	v_and_b32_e32 v88, 0xffff0000, v31
	v_fmac_f32_e32 v25, v87, v87
	v_lshlrev_b32_e32 v89, 16, v32
	v_fmac_f32_e32 v25, v88, v88
	v_and_b32_e32 v90, 0xffff0000, v32
	v_fmac_f32_e32 v25, v89, v89
	v_lshlrev_b32_e32 v91, 16, v33
	v_fmac_f32_e32 v25, v90, v90
	v_and_b32_e32 v92, 0xffff0000, v33
	v_fmac_f32_e32 v25, v91, v91
	v_lshlrev_b32_e32 v64, 16, v26
	v_fmac_f32_e32 v25, v92, v92
	v_and_b32_e32 v63, 0xffff0000, v26
	v_fmac_f32_e32 v25, v64, v64
	v_lshlrev_b32_e32 v61, 16, v27
	v_fmac_f32_e32 v25, v63, v63
	v_and_b32_e32 v60, 0xffff0000, v27
	v_fmac_f32_e32 v25, v61, v61
	v_lshlrev_b32_e32 v59, 16, v28
	v_fmac_f32_e32 v25, v60, v60
	v_and_b32_e32 v58, 0xffff0000, v28
	v_fmac_f32_e32 v25, v59, v59
	v_lshlrev_b32_e32 v57, 16, v29
	v_fmac_f32_e32 v25, v58, v58
	v_and_b32_e32 v56, 0xffff0000, v29
	v_fmac_f32_e32 v25, v57, v57
	v_fmac_f32_e32 v25, v56, v56
	v_fmac_f32_e32 v25, v55, v55
	v_fmac_f32_e32 v25, v54, v54
	v_fmac_f32_e32 v25, v53, v53
	v_lshlrev_b32_e32 v51, 16, v24
	v_fmac_f32_e32 v25, v52, v52
	v_and_b32_e32 v24, 0xffff0000, v24
	v_fmac_f32_e32 v25, v51, v51
	v_fmac_f32_e32 v25, v24, v24
	v_fmac_f32_e32 v25, v23, v23
	v_lshlrev_b32_e32 v33, 16, v18
	v_fmac_f32_e32 v25, v22, v22
	v_and_b32_e32 v32, 0xffff0000, v18
	v_fmac_f32_e32 v25, v33, v33
	v_lshlrev_b32_e32 v31, 16, v19
	v_fmac_f32_e32 v25, v32, v32
	v_and_b32_e32 v30, 0xffff0000, v19
	v_fmac_f32_e32 v25, v31, v31
	v_and_b32_e32 v28, 0xffff0000, v20
	v_lshlrev_b32_e32 v29, 16, v20
	v_fmac_f32_e32 v25, v30, v30
	v_pk_mul_f32 v[18:19], v[28:29], v[28:29]
	v_and_b32_e32 v26, 0xffff0000, v21
	v_add_f32_e32 v19, v19, v25
	v_lshlrev_b32_e32 v27, 16, v21
	v_add_f32_e32 v20, v18, v19
	v_pk_mul_f32 v[18:19], v[26:27], v[26:27]
	s_nop 0
	v_add_f32_e32 v19, v19, v20
	v_add_f32_e32 v18, v18, v19
	ds_bpermute_b32 v19, v199, v18
	s_waitcnt lgkmcnt(0)
	v_add_f32_e32 v18, v18, v19
	v_fmamk_f32 v18, v18, 0x3c800000, v202
	v_rsq_f32_e32 v18, v18
	s_nop 0
	v_mul_f32_e32 v50, 0x3e38aa3b, v18
	v_mov_b64_e32 v[18:19], v[220:221]
	v_mov_b64_e32 v[20:21], v[222:223]
	v_mov_b64_e32 v[82:83], v[216:217]
	v_mov_b64_e32 v[84:85], v[218:219]
	v_mul_f32_e32 v25, v50, v65
	v_mul_f32_e32 v65, v50, v86
	v_mul_f32_e32 v63, v50, v63
	v_mul_f32_e32 v60, v50, v60
	v_mul_f32_e32 v54, v50, v54
	v_mul_f32_e32 v52, v50, v52
	v_mul_f32_e32 v24, v50, v24
	v_mul_f32_e32 v33, v50, v33
	v_mul_f32_e32 v32, v50, v32
	s_waitcnt vmcnt(0)
	v_mul_f32_e32 v25, v82, v25
	v_mul_f32_e32 v65, v83, v65
	v_cvt_pk_bf16_f32 v114, v25, v65
	v_mul_f32_e32 v25, v50, v87
	v_mul_f32_e32 v25, v84, v25
	v_mul_f32_e32 v65, v50, v88
	v_mul_f32_e32 v65, v85, v65
	v_cvt_pk_bf16_f32 v115, v25, v65
	v_mul_f32_e32 v25, v50, v89
	v_mul_f32_e32 v18, v18, v25
	v_mul_f32_e32 v25, v50, v90
	v_mul_f32_e32 v19, v19, v25
	v_cvt_pk_bf16_f32 v116, v18, v19
	v_mul_f32_e32 v18, v50, v91
	v_mul_f32_e32 v19, v50, v92
	v_mul_f32_e32 v18, v20, v18
	v_mul_f32_e32 v19, v21, v19
	v_cvt_pk_bf16_f32 v117, v18, v19
	v_mov_b64_e32 v[18:19], v[228:229]
	v_mov_b64_e32 v[20:21], v[230:231]
	v_mov_b64_e32 v[82:83], v[224:225]
	v_mov_b64_e32 v[84:85], v[226:227]
	v_mul_f32_e32 v25, v50, v64
	s_waitcnt vmcnt(0)
	v_mul_f32_e32 v25, v25, v82
	v_mul_f32_e32 v63, v63, v83
	v_cvt_pk_bf16_f32 v162, v25, v63
	v_mul_f32_e32 v25, v50, v61
	v_mul_f32_e32 v25, v25, v84
	v_mul_f32_e32 v60, v60, v85
	v_cvt_pk_bf16_f32 v163, v25, v60
	v_mul_f32_e32 v25, v50, v59
	v_mul_f32_e32 v18, v25, v18
	v_mul_f32_e32 v25, v50, v58
	v_mul_f32_e32 v19, v25, v19
	v_cvt_pk_bf16_f32 v164, v18, v19
	v_mul_f32_e32 v18, v50, v57
	v_mul_f32_e32 v19, v50, v56
	v_mul_f32_e32 v18, v18, v20
	v_mul_f32_e32 v19, v19, v21
	v_cvt_pk_bf16_f32 v165, v18, v19
	v_mov_b64_e32 v[18:19], v[236:237]
	v_mov_b64_e32 v[20:21], v[238:239]
	v_mov_b64_e32 v[56:57], v[232:233]
	v_mov_b64_e32 v[58:59], v[234:235]
	v_mul_f32_e32 v25, v50, v55
	s_waitcnt vmcnt(1)
	v_mul_f32_e32 v19, v24, v19
	s_waitcnt vmcnt(0)
	v_mul_f32_e32 v25, v25, v56
	v_mul_f32_e32 v54, v54, v57
	v_cvt_pk_bf16_f32 v166, v25, v54
	v_mul_f32_e32 v25, v50, v53
	v_mul_f32_e32 v25, v25, v58
	v_mul_f32_e32 v52, v52, v59
	v_cvt_pk_bf16_f32 v167, v25, v52
	v_mul_f32_e32 v25, v50, v51
	v_mul_f32_e32 v18, v25, v18
	v_cvt_pk_bf16_f32 v168, v18, v19
	v_mul_f32_e32 v18, v50, v23
	v_mul_f32_e32 v19, v50, v22
	v_mul_f32_e32 v18, v18, v20
	v_mul_f32_e32 v19, v19, v21
	v_cvt_pk_bf16_f32 v169, v18, v19
	v_mov_b64_e32 v[18:19], v[248:249]
	v_mov_b64_e32 v[20:21], v[250:251]
	v_mov_b64_e32 v[22:23], v[240:241]
	v_mov_b64_e32 v[24:25], v[242:243]
	s_waitcnt vmcnt(0)
	v_readlane_b32 s20, v247, 7
	v_readlane_b32 s21, v247, 33
	v_lshrrev_b32_e32 v82, 1, v194
	v_and_b32_e32 v83, 1, v194
	s_and_b32 s32, s20, 1
	s_lshl_b32 s21, s21, 1
	s_add_i32 s21, s21, s32
	s_lshl_b32 s21, s21, 5
	s_add_i32 s21, s21, -15
	v_add_u32_e32 v84, 32, v82
	v_min_u32_e32 v84, 46, v84
	v_add_u32_e32 v85, s21, v82
	v_add_u32_e32 v84, s21, v84
	s_lshr_b32 s21, s20, 1
	s_lshl_b32 s21, s21, 8
	v_max_i32_e32 v85, 0, v85
	v_max_i32_e32 v84, 0, v84
	v_mul_u32_u24_e32 v85, 0x1a00, v85
	v_mul_u32_u24_e32 v84, 0x1a00, v84
	v_lshl_add_u32 v85, v83, 7, v85
	v_lshl_add_u32 v84, v83, 7, v84
	v_add_u32_e32 v85, s21, v85
	v_add_u32_e32 v84, s21, v84
	s_lshl_b32 s32, s20, 9
	s_cmp_lt_u32 s20, 4
	s_cbranch_scc1 .Lp2pf_kv
	s_add_i32 m0, s32, 0x22000
	s_nop 0
	global_load_lds_dword v85, s[92:93]
	s_add_i32 m0, s32, 0x22100
	s_nop 0
	global_load_lds_dword v84, s[92:93]
.Lp2pf_kv:
	s_cmp_gt_u32 s20, 3
	s_cbranch_scc1 .Lp2pf_done
	v_readlane_b32 s21, v247, 33
	s_lshl_b32 s32, s20, 6
	v_lshl_add_u32 v84, v82, 1, s32
	s_and_b32 s32, s21, 1
	s_lshr_b32 s21, s21, 1
	v_add_u32_e32 v84, s32, v84
	s_lshl_b32 s21, s21, 16
	v_lshlrev_b32_e32 v84, 8, v84
	v_lshl_add_u32 v84, v83, 7, v84
	v_add_u32_e32 v84, s21, v84
	s_lshl_b32 s32, s20, 9
	s_add_i32 m0, s32, 0x23000
	s_nop 0
	global_load_lds_dword v84, s[84:85]
	s_add_i32 m0, s32, 0x23100
	s_nop 0
	global_load_lds_dword v84, s[86:87]
